# out-projection GEMM main loop: 4/4/4/4 LDS-DMA loads per load segment as well
# speedup vs baseline: 1.0157x; 1.0042x over previous
.LBB0_1259:
	s_add_u32 s22, s92, s76
	s_addc_u32 s23, s93, s77
	s_add_u32 s80, s96, s76
	s_addc_u32 s81, s97, s77
	s_cmp_eq_u32 s44, 0
	s_cselect_b32 s23, s15, s23
	s_cselect_b32 s22, s91, s22
	s_cselect_b32 vcc_hi, s89, s81
	s_cselect_b32 vcc_lo, s8, s80
	s_add_u32 s80, s92, s76
	s_addc_u32 s81, s93, s77
	s_sub_u32 s80, s80, 0x80
	s_subb_u32 s81, s81, 0
	s_add_i32 s83, 0, 0x14000
	ds_read_b128 v[142:145], v222
	ds_read_b128 v[146:149], v222 offset:1024
	ds_read_b128 v[150:153], v222 offset:2048
	ds_read_b128 v[154:157], v222 offset:3072
	ds_read_b128 v[158:161], v223
	ds_read_b128 v[162:165], v223 offset:1024
	ds_read_b128 v[166:169], v223 offset:2048
	ds_read_b128 v[170:173], v223 offset:3072
	s_mov_b32 m0, s9
	ds_read_b128 v[174:177], v140
	ds_read_b128 v[178:181], v140 offset:1024
	ds_read_b128 v[182:185], v140 offset:2048
	ds_read_b128 v[186:189], v140 offset:3072
	ds_read_b128 v[190:193], v140 offset:4096
	ds_read_b128 v[194:197], v140 offset:5120
	ds_read_b128 v[198:201], v140 offset:6144
	ds_read_b128 v[202:205], v140 offset:7168
	global_load_lds_dwordx4 v208, s[80:81]
	s_mov_b32 m0, s12
	s_nop 0
	global_load_lds_dwordx4 v128, s[80:81]
	s_add_i32 m0, s45, 0xc000
	s_nop 0
	global_load_lds_dwordx4 v136, s[92:93]
	s_add_i32 m0, s45, 0xe000
	s_nop 0
	global_load_lds_dwordx4 v134, s[92:93]
	s_waitcnt vmcnt(8)
	s_waitcnt lgkmcnt(0)
	s_barrier
	v_mfma_f32_16x16x32_bf16 v[124:127], v[142:145], v[174:177], v[124:127]
	v_mfma_f32_16x16x32_bf16 v[120:123], v[150:153], v[174:177], v[120:123]
	v_mfma_f32_16x16x32_bf16 v[108:111], v[142:145], v[182:185], v[108:111]
	v_mfma_f32_16x16x32_bf16 v[104:107], v[150:153], v[182:185], v[104:107]
	v_mfma_f32_16x16x32_bf16 v[92:95], v[142:145], v[190:193], v[92:95]
	v_mfma_f32_16x16x32_bf16 v[88:91], v[150:153], v[190:193], v[88:91]
	v_mfma_f32_16x16x32_bf16 v[76:79], v[142:145], v[198:201], v[76:79]
	v_mfma_f32_16x16x32_bf16 v[72:75], v[150:153], v[198:201], v[72:75]
	v_mfma_f32_16x16x32_bf16 v[124:127], v[146:149], v[178:181], v[124:127]
	v_mfma_f32_16x16x32_bf16 v[120:123], v[154:157], v[178:181], v[120:123]
	v_mfma_f32_16x16x32_bf16 v[108:111], v[146:149], v[186:189], v[108:111]
	v_mfma_f32_16x16x32_bf16 v[104:107], v[154:157], v[186:189], v[104:107]
	v_mfma_f32_16x16x32_bf16 v[92:95], v[146:149], v[194:197], v[92:95]
	v_mfma_f32_16x16x32_bf16 v[88:91], v[154:157], v[194:197], v[88:91]
	v_mfma_f32_16x16x32_bf16 v[76:79], v[146:149], v[202:205], v[76:79]
	v_mfma_f32_16x16x32_bf16 v[72:75], v[154:157], v[202:205], v[72:75]
	v_mfma_f32_16x16x32_bf16 v[116:119], v[158:161], v[174:177], v[116:119]
	v_mfma_f32_16x16x32_bf16 v[112:115], v[166:169], v[174:177], v[112:115]
	v_mfma_f32_16x16x32_bf16 v[100:103], v[158:161], v[182:185], v[100:103]
	v_mfma_f32_16x16x32_bf16 v[96:99], v[166:169], v[182:185], v[96:99]
	v_mfma_f32_16x16x32_bf16 v[84:87], v[158:161], v[190:193], v[84:87]
	v_mfma_f32_16x16x32_bf16 v[80:83], v[166:169], v[190:193], v[80:83]
	v_mfma_f32_16x16x32_bf16 v[68:71], v[158:161], v[198:201], v[68:71]
	v_mfma_f32_16x16x32_bf16 v[64:67], v[166:169], v[198:201], v[64:67]
	v_mfma_f32_16x16x32_bf16 v[116:119], v[162:165], v[178:181], v[116:119]
	v_mfma_f32_16x16x32_bf16 v[112:115], v[170:173], v[178:181], v[112:115]
	v_mfma_f32_16x16x32_bf16 v[100:103], v[162:165], v[186:189], v[100:103]
	v_mfma_f32_16x16x32_bf16 v[96:99], v[170:173], v[186:189], v[96:99]
	v_mfma_f32_16x16x32_bf16 v[84:87], v[162:165], v[194:197], v[84:87]
	v_mfma_f32_16x16x32_bf16 v[80:83], v[170:173], v[194:197], v[80:83]
	v_mfma_f32_16x16x32_bf16 v[68:71], v[162:165], v[202:205], v[68:71]
	v_mfma_f32_16x16x32_bf16 v[64:67], v[170:173], v[202:205], v[64:67]
	s_barrier
	s_add_i32 s80, s43, 0x10000
	s_mov_b32 m0, s80
	ds_read_b128 v[174:177], v140 offset:16384
	ds_read_b128 v[178:181], v140 offset:17408
	ds_read_b128 v[182:185], v140 offset:18432
	ds_read_b128 v[186:189], v140 offset:19456
	ds_read_b128 v[190:193], v140 offset:20480
	ds_read_b128 v[194:197], v140 offset:21504
	ds_read_b128 v[198:201], v140 offset:22528
	ds_read_b128 v[202:205], v140 offset:23552
	global_load_lds_dwordx4 v208, vcc
	s_add_i32 m0, s80, 0x2000
	s_add_u32 s80, vcc_lo, 0x80000
	s_addc_u32 s81, vcc_hi, 0
	s_add_i32 s83, s83, s43
	global_load_lds_dwordx4 v128, vcc
	s_mov_b32 m0, s83
	s_nop 0
	global_load_lds_dwordx4 v208, s[80:81]
	s_add_i32 m0, s83, 0x2000
	s_nop 0
	global_load_lds_dwordx4 v128, s[80:81]
	s_waitcnt vmcnt(6)
	s_waitcnt lgkmcnt(0)
	s_barrier
	v_mfma_f32_16x16x32_bf16 v[60:63], v[142:145], v[174:177], v[60:63]
	v_mfma_f32_16x16x32_bf16 v[56:59], v[150:153], v[174:177], v[56:59]
	v_mfma_f32_16x16x32_bf16 v[44:47], v[142:145], v[182:185], v[44:47]
	v_mfma_f32_16x16x32_bf16 v[40:43], v[150:153], v[182:185], v[40:43]
	v_mfma_f32_16x16x32_bf16 v[28:31], v[142:145], v[190:193], v[28:31]
	v_mfma_f32_16x16x32_bf16 v[24:27], v[150:153], v[190:193], v[24:27]
	v_mfma_f32_16x16x32_bf16 v[12:15], v[142:145], v[198:201], v[12:15]
	v_mfma_f32_16x16x32_bf16 v[8:11], v[150:153], v[198:201], v[8:11]
	v_mfma_f32_16x16x32_bf16 v[60:63], v[146:149], v[178:181], v[60:63]
	v_mfma_f32_16x16x32_bf16 v[56:59], v[154:157], v[178:181], v[56:59]
	v_mfma_f32_16x16x32_bf16 v[44:47], v[146:149], v[186:189], v[44:47]
	v_mfma_f32_16x16x32_bf16 v[40:43], v[154:157], v[186:189], v[40:43]
	v_mfma_f32_16x16x32_bf16 v[28:31], v[146:149], v[194:197], v[28:31]
	v_mfma_f32_16x16x32_bf16 v[24:27], v[154:157], v[194:197], v[24:27]
	v_mfma_f32_16x16x32_bf16 v[12:15], v[146:149], v[202:205], v[12:15]
	v_mfma_f32_16x16x32_bf16 v[8:11], v[154:157], v[202:205], v[8:11]
	v_mfma_f32_16x16x32_bf16 v[52:55], v[158:161], v[174:177], v[52:55]
	v_mfma_f32_16x16x32_bf16 v[48:51], v[166:169], v[174:177], v[48:51]
	v_mfma_f32_16x16x32_bf16 v[36:39], v[158:161], v[182:185], v[36:39]
	v_mfma_f32_16x16x32_bf16 v[32:35], v[166:169], v[182:185], v[32:35]
	v_mfma_f32_16x16x32_bf16 v[20:23], v[158:161], v[190:193], v[20:23]
	v_mfma_f32_16x16x32_bf16 v[16:19], v[166:169], v[190:193], v[16:19]
	v_mfma_f32_16x16x32_bf16 v[4:7], v[158:161], v[198:201], v[4:7]
	v_mfma_f32_16x16x32_bf16 v[0:3], v[166:169], v[198:201], v[0:3]
	v_mfma_f32_16x16x32_bf16 v[52:55], v[162:165], v[178:181], v[52:55]
	v_mfma_f32_16x16x32_bf16 v[48:51], v[170:173], v[178:181], v[48:51]
	v_mfma_f32_16x16x32_bf16 v[36:39], v[162:165], v[186:189], v[36:39]
	v_mfma_f32_16x16x32_bf16 v[32:35], v[170:173], v[186:189], v[32:35]
	v_mfma_f32_16x16x32_bf16 v[20:23], v[162:165], v[194:197], v[20:23]
	v_mfma_f32_16x16x32_bf16 v[16:19], v[170:173], v[194:197], v[16:19]
	v_mfma_f32_16x16x32_bf16 v[4:7], v[162:165], v[202:205], v[4:7]
	v_mfma_f32_16x16x32_bf16 v[0:3], v[170:173], v[202:205], v[0:3]
	s_barrier
	s_add_i32 s80, 0, 0x18000
	s_add_i32 s81, 0, 0x1c000
	ds_read_b128 v[142:145], v224
	ds_read_b128 v[146:149], v224 offset:1024
	ds_read_b128 v[150:153], v224 offset:2048
	ds_read_b128 v[154:157], v224 offset:3072
	ds_read_b128 v[158:161], v225
	ds_read_b128 v[162:165], v225 offset:1024
	ds_read_b128 v[166:169], v225 offset:2048
	ds_read_b128 v[170:173], v225 offset:3072
	ds_read_b128 v[174:177], v140 offset:32768
	ds_read_b128 v[178:181], v140 offset:33792
	ds_read_b128 v[182:185], v140 offset:34816
	ds_read_b128 v[186:189], v140 offset:35840
	ds_read_b128 v[190:193], v140 offset:36864
	ds_read_b128 v[194:197], v140 offset:37888
	ds_read_b128 v[198:201], v140 offset:38912
	ds_read_b128 v[202:205], v140 offset:39936
	s_mov_b32 m0, s45
	s_nop 0
	global_load_lds_dwordx4 v208, s[22:23]
	s_mov_b32 m0, s52
	s_nop 0
	global_load_lds_dwordx4 v128, s[22:23]
	s_mov_b32 m0, s53
	s_add_u32 s22, s22, 0x80000
	s_addc_u32 s23, s23, 0
	global_load_lds_dwordx4 v208, s[22:23]
	s_mov_b32 m0, s85
	s_nop 0
	global_load_lds_dwordx4 v128, s[22:23]
	s_waitcnt vmcnt(8)
	s_waitcnt lgkmcnt(0)
	s_barrier
	v_mfma_f32_16x16x32_bf16 v[124:127], v[142:145], v[174:177], v[124:127]
	v_mfma_f32_16x16x32_bf16 v[120:123], v[150:153], v[174:177], v[120:123]
	v_mfma_f32_16x16x32_bf16 v[108:111], v[142:145], v[182:185], v[108:111]
	v_mfma_f32_16x16x32_bf16 v[104:107], v[150:153], v[182:185], v[104:107]
	v_mfma_f32_16x16x32_bf16 v[92:95], v[142:145], v[190:193], v[92:95]
	v_mfma_f32_16x16x32_bf16 v[88:91], v[150:153], v[190:193], v[88:91]
	v_mfma_f32_16x16x32_bf16 v[76:79], v[142:145], v[198:201], v[76:79]
	v_mfma_f32_16x16x32_bf16 v[72:75], v[150:153], v[198:201], v[72:75]
	v_mfma_f32_16x16x32_bf16 v[124:127], v[146:149], v[178:181], v[124:127]
	v_mfma_f32_16x16x32_bf16 v[120:123], v[154:157], v[178:181], v[120:123]
	v_mfma_f32_16x16x32_bf16 v[108:111], v[146:149], v[186:189], v[108:111]
	v_mfma_f32_16x16x32_bf16 v[104:107], v[154:157], v[186:189], v[104:107]
	v_mfma_f32_16x16x32_bf16 v[92:95], v[146:149], v[194:197], v[92:95]
	v_mfma_f32_16x16x32_bf16 v[88:91], v[154:157], v[194:197], v[88:91]
	v_mfma_f32_16x16x32_bf16 v[76:79], v[146:149], v[202:205], v[76:79]
	v_mfma_f32_16x16x32_bf16 v[72:75], v[154:157], v[202:205], v[72:75]
	v_mfma_f32_16x16x32_bf16 v[116:119], v[158:161], v[174:177], v[116:119]
	v_mfma_f32_16x16x32_bf16 v[112:115], v[166:169], v[174:177], v[112:115]
	v_mfma_f32_16x16x32_bf16 v[100:103], v[158:161], v[182:185], v[100:103]
	v_mfma_f32_16x16x32_bf16 v[96:99], v[166:169], v[182:185], v[96:99]
	v_mfma_f32_16x16x32_bf16 v[84:87], v[158:161], v[190:193], v[84:87]
	v_mfma_f32_16x16x32_bf16 v[80:83], v[166:169], v[190:193], v[80:83]
	v_mfma_f32_16x16x32_bf16 v[68:71], v[158:161], v[198:201], v[68:71]
	v_mfma_f32_16x16x32_bf16 v[64:67], v[166:169], v[198:201], v[64:67]
	v_mfma_f32_16x16x32_bf16 v[116:119], v[162:165], v[178:181], v[116:119]
	v_mfma_f32_16x16x32_bf16 v[112:115], v[170:173], v[178:181], v[112:115]
	v_mfma_f32_16x16x32_bf16 v[100:103], v[162:165], v[186:189], v[100:103]
	v_mfma_f32_16x16x32_bf16 v[96:99], v[170:173], v[186:189], v[96:99]
	v_mfma_f32_16x16x32_bf16 v[84:87], v[162:165], v[194:197], v[84:87]
	v_mfma_f32_16x16x32_bf16 v[80:83], v[170:173], v[194:197], v[80:83]
	v_mfma_f32_16x16x32_bf16 v[68:71], v[162:165], v[202:205], v[68:71]
	v_mfma_f32_16x16x32_bf16 v[64:67], v[170:173], v[202:205], v[64:67]
	s_barrier
	s_add_i32 s22, s80, s43
	s_add_i32 m0, s22, 0xffffff80
	ds_read_b128 v[174:177], v140 offset:49152
	ds_read_b128 v[178:181], v140 offset:50176
	ds_read_b128 v[182:185], v140 offset:51200
	ds_read_b128 v[186:189], v140 offset:52224
	ds_read_b128 v[190:193], v140 offset:53248
	ds_read_b128 v[194:197], v140 offset:54272
	ds_read_b128 v[198:201], v140 offset:55296
	ds_read_b128 v[202:205], v140 offset:56320
	global_load_lds_dwordx4 v208, vcc offset:128
	s_add_i32 m0, s22, 0x1f80
	s_add_u32 s22, vcc_lo, 0x80080
	s_addc_u32 s23, vcc_hi, 0
	s_add_i32 s80, s81, s43
	global_load_lds_dwordx4 v128, vcc offset:128
	s_mov_b32 m0, s80
	s_nop 0
	global_load_lds_dwordx4 v208, s[22:23]
	s_add_i32 m0, s80, 0x2000
	s_nop 0
	global_load_lds_dwordx4 v128, s[22:23]
	s_waitcnt vmcnt(6)
	s_waitcnt lgkmcnt(0)
	s_barrier
	v_mfma_f32_16x16x32_bf16 v[60:63], v[142:145], v[174:177], v[60:63]
	v_mfma_f32_16x16x32_bf16 v[56:59], v[150:153], v[174:177], v[56:59]
	v_mfma_f32_16x16x32_bf16 v[44:47], v[142:145], v[182:185], v[44:47]
	v_mfma_f32_16x16x32_bf16 v[40:43], v[150:153], v[182:185], v[40:43]
	v_mfma_f32_16x16x32_bf16 v[28:31], v[142:145], v[190:193], v[28:31]
	v_mfma_f32_16x16x32_bf16 v[24:27], v[150:153], v[190:193], v[24:27]
	v_mfma_f32_16x16x32_bf16 v[12:15], v[142:145], v[198:201], v[12:15]
	v_mfma_f32_16x16x32_bf16 v[8:11], v[150:153], v[198:201], v[8:11]
	v_mfma_f32_16x16x32_bf16 v[60:63], v[146:149], v[178:181], v[60:63]
	v_mfma_f32_16x16x32_bf16 v[56:59], v[154:157], v[178:181], v[56:59]
	v_mfma_f32_16x16x32_bf16 v[44:47], v[146:149], v[186:189], v[44:47]
	v_mfma_f32_16x16x32_bf16 v[40:43], v[154:157], v[186:189], v[40:43]
	v_mfma_f32_16x16x32_bf16 v[28:31], v[146:149], v[194:197], v[28:31]
	v_mfma_f32_16x16x32_bf16 v[24:27], v[154:157], v[194:197], v[24:27]
	v_mfma_f32_16x16x32_bf16 v[12:15], v[146:149], v[202:205], v[12:15]
	v_mfma_f32_16x16x32_bf16 v[8:11], v[154:157], v[202:205], v[8:11]
	v_mfma_f32_16x16x32_bf16 v[52:55], v[158:161], v[174:177], v[52:55]
	v_mfma_f32_16x16x32_bf16 v[48:51], v[166:169], v[174:177], v[48:51]
	v_mfma_f32_16x16x32_bf16 v[36:39], v[158:161], v[182:185], v[36:39]
	v_mfma_f32_16x16x32_bf16 v[32:35], v[166:169], v[182:185], v[32:35]
	v_mfma_f32_16x16x32_bf16 v[20:23], v[158:161], v[190:193], v[20:23]
	v_mfma_f32_16x16x32_bf16 v[16:19], v[166:169], v[190:193], v[16:19]
	v_mfma_f32_16x16x32_bf16 v[4:7], v[158:161], v[198:201], v[4:7]
	v_mfma_f32_16x16x32_bf16 v[0:3], v[166:169], v[198:201], v[0:3]
	v_mfma_f32_16x16x32_bf16 v[52:55], v[162:165], v[178:181], v[52:55]
	v_mfma_f32_16x16x32_bf16 v[48:51], v[170:173], v[178:181], v[48:51]
	v_mfma_f32_16x16x32_bf16 v[36:39], v[162:165], v[186:189], v[36:39]
	v_mfma_f32_16x16x32_bf16 v[32:35], v[170:173], v[186:189], v[32:35]
	v_mfma_f32_16x16x32_bf16 v[20:23], v[162:165], v[194:197], v[20:23]
	v_mfma_f32_16x16x32_bf16 v[16:19], v[170:173], v[194:197], v[16:19]
	v_mfma_f32_16x16x32_bf16 v[4:7], v[162:165], v[202:205], v[4:7]
	v_mfma_f32_16x16x32_bf16 v[0:3], v[170:173], v[202:205], v[0:3]
	s_barrier
	s_addk_i32 s44, 0x200
	s_add_u32 s76, s76, 0x100
	s_addc_u32 s77, s77, 0
	s_add_i32 s22, s82, 2
	v_lshl_add_u64 v[136:137], v[136:137], 0, s[58:59]
	s_cmp_gt_u32 s82, 29
	v_lshl_add_u64 v[134:135], v[134:135], 0, s[58:59]
	s_cbranch_scc1 .LBB0_1261
	s_mov_b32 s82, s22
	s_branch .LBB0_1257
